# v4 + per-tile static-order arithmetic specialised (no float-rcp division; groups are always 8 rows)
# baseline (speedup 1.0000x reference)
;     __device__ bool next(int i, Unit& u) const {
;         const long L = (long)i * G + c; if (L >= nwg) return false;
;         int wgid = (int)L; { const int q = nwg / NXCD, r = nwg % NXCD, xcd = wgid % NXCD, off = wgid / NXCD; wgid = (xcd < r ? xcd * (q + 1) : r * (q + 1) + (xcd - r) * q) + off; }
;         const int nig = WGM * nN, gid = wgid / nig, fm = gid * WGM, gsz = (nM - fm) < WGM ? (nM - fm) : WGM;
;         u.pm = fm + ((wgid % nig) % gsz); u.pn = (wgid % nig) / gsz; return true;
;     }
.Lcw_noptr:
	s_add_i32 s68, s68, 1
	s_mul_i32 s1, s68, s15
	s_mul_hi_u32 s3, s68, s14
	s_add_i32 s3, s3, s1
	s_mul_i32 s1, s68, s14
	s_add_u32 s8, s1, s2
	s_addc_u32 s9, s3, s37
	v_mov_b64_e32 v[0:1], s[30:31]
	v_cmp_ge_i64_e64 s[4:5], s[8:9], v[0:1]
	v_cmp_lt_i64_e64 s[6:7], s[8:9], v[0:1]
	s_and_b64 vcc, exec, s[4:5]
	s_cbranch_vccnz .LBB0_329
	s_and_b32 s1, s8, 7
	s_lshr_b32 s3, s8, 3
	s_mul_i32 s1, s1, s60
	s_add_i32 s1, s1, s3
	s_mul_hi_u32 s9, s1, s69
	s_mul_i32 s12, s9, s55
	s_sub_i32 s8, s1, s12
	s_add_i32 s12, s9, 1
	s_sub_i32 s13, s8, s55
	s_cmp_ge_u32 s8, s55
	s_cselect_b32 s9, s12, s9
	s_cselect_b32 s8, s13, s8
	s_add_i32 s12, s9, 1
	s_sub_i32 s13, s8, s55
	s_cmp_ge_u32 s8, s55
	s_cselect_b32 s9, s12, s9
	s_cselect_b32 s8, s13, s8
	s_lshr_b32 s70, s8, 3
	s_and_b32 s8, s8, 7
	s_lshl_b32 s9, s9, 3
	s_add_i32 s71, s9, s8
